# packed fp32 ops between the QK^T and P.V MFMA groups split into single v_add/v_sub (FoX bias + reference subtraction, differential reference subtraction)
# baseline (speedup 1.0000x reference)
; __device__ __forceinline__ void biasf(f32x16&p0,f32x16&p1,const __attribute__((address_space(3))) float*p){
;   #pragma unroll
;   for(int j=0;j<4;++j){ const f32x4a a=*(const __attribute__((address_space(3))) f32x4a*)(p+8*j), b=*(const __attribute__((address_space(3))) f32x4a*)(p+32+8*j);
;     p0[4*j]+=a[0];p0[4*j+1]+=a[1];p0[4*j+2]+=a[2];p0[4*j+3]+=a[3]; p1[4*j]+=b[0];p1[4*j+1]+=b[1];p1[4*j+2]+=b[2];p1[4*j+3]+=b[3];
;     asm volatile("":"+v"(p0),"+v"(p1)); __builtin_amdgcn_sched_barrier(0); }
; }
; __device__ __forceinline__ void biasd(f32x16&p0,f32x16&p1,const __attribute__((address_space(3))) float*lut,int base){
;   #pragma unroll
;   for(int r=0;r<16;++r){ const int d0=base-((r&3)+8*(r>>2)); unsigned i0=(unsigned)d0; i0=i0>127u?127u:i0; unsigned i1=(unsigned)(d0-32); i1=i1>127u?127u:i1; p0[r]+=lut[i0]; p1[r]+=lut[i1];
;     if((r&3)==3){ asm volatile("":"+v"(p0),"+v"(p1)); __builtin_amdgcn_sched_barrier(0); } }
; }
; __device__ __forceinline__ void submh(f32x16&p0,f32x16&p1,float mh){ const f32x2a m2={mh,mh};
;   #pragma unroll
;   for(int r=0;r<16;r+=2){ f32x2a a={p0[r],p0[r+1]}, b={p1[r],p1[r+1]}; a=a-m2; b=b-m2; p0[r]=a[0];p0[r+1]=a[1];p1[r]=b[0];p1[r+1]=b[1]; }
; }
.LBB0_383:
	ds_read_b128 v[222:225], v184
	ds_read_b128 v[226:229], v184 offset:128
	ds_read_b128 v[230:233], v184 offset:32
	ds_read_b128 v[242:245], v184 offset:160
	ds_read_b128 v[246:249], v184 offset:64
	ds_read_b128 v[250:253], v184 offset:192
	v_add_u32_e32 v0, s56, v219
	ds_read_b64_tr_b16 v[176:177], v0 offset:24576
	ds_read_b64_tr_b16 v[178:179], v0 offset:25088
	v_add_f32_e32 v2, v64, v65
	v_add_f32_e32 v2, v66, v2
	v_add_f32_e32 v2, v67, v2
	v_add_f32_e32 v2, v68, v2
	v_add_f32_e32 v2, v69, v2
	v_cvt_pk_bf16_f32 v132, v64, v65
	v_cvt_pk_bf16_f32 v133, v66, v67
	s_waitcnt lgkmcnt(9)
	v_mfma_f32_32x32x16_bf16 v[80:95], v[172:175], v[140:143], 0
	ds_read_b64_tr_b16 v[172:173], v0 offset:28672
	ds_read_b64_tr_b16 v[174:175], v0 offset:29184
	v_add_f32_e32 v2, v70, v2
	v_add_f32_e32 v2, v71, v2
	v_add_f32_e32 v2, v72, v2
	v_add_f32_e32 v2, v73, v2
	v_cvt_pk_bf16_f32 v134, v68, v69
	v_cvt_pk_bf16_f32 v135, v70, v71
	s_waitcnt lgkmcnt(10)
	v_mfma_f32_32x32x16_bf16 v[96:111], v[168:171], v[140:143], 0
	ds_read_b64_tr_b16 v[168:169], v0 offset:25600
	ds_read_b64_tr_b16 v[170:171], v0 offset:26112
	v_add_f32_e32 v2, v74, v2
	v_add_f32_e32 v2, v75, v2
	v_add_f32_e32 v2, v76, v2
	v_add_f32_e32 v2, v77, v2
	v_cvt_pk_bf16_f32 v124, v72, v73
	v_cvt_pk_bf16_f32 v125, v74, v75
	s_waitcnt lgkmcnt(11)
	v_mfma_f32_32x32x16_bf16 v[80:95], v[164:167], v[136:139], v[80:95]
	ds_read_b64_tr_b16 v[164:165], v0 offset:29696
	ds_read_b64_tr_b16 v[166:167], v0 offset:30208
	v_add_f32_e32 v2, v78, v2
	v_add_f32_e32 v2, v79, v2
	v_add_f32_e32 v2, v48, v2
	v_add_f32_e32 v2, v49, v2
	v_cvt_pk_bf16_f32 v126, v76, v77
	v_cvt_pk_bf16_f32 v127, v78, v79
	s_waitcnt lgkmcnt(12)
	v_mfma_f32_32x32x16_bf16 v[96:111], v[160:163], v[136:139], v[96:111]
	ds_read_b64_tr_b16 v[160:161], v0 offset:26624
	ds_read_b64_tr_b16 v[162:163], v0 offset:27136
	v_add_f32_e32 v2, v50, v2
	v_add_f32_e32 v2, v51, v2
	v_add_f32_e32 v2, v52, v2
	v_add_f32_e32 v2, v53, v2
	v_cvt_pk_bf16_f32 v116, v48, v49
	v_cvt_pk_bf16_f32 v117, v50, v51
	s_waitcnt lgkmcnt(13)
	v_mfma_f32_32x32x16_bf16 v[80:95], v[156:159], v[128:131], v[80:95]
	ds_read_b64_tr_b16 v[10:11], v0 offset:30720
	ds_read_b64_tr_b16 v[12:13], v0 offset:31232
	v_add_f32_e32 v2, v54, v2
	v_add_f32_e32 v2, v55, v2
	v_add_f32_e32 v2, v56, v2
	v_add_f32_e32 v2, v57, v2
	v_cvt_pk_bf16_f32 v118, v52, v53
	v_cvt_pk_bf16_f32 v119, v54, v55
	s_waitcnt lgkmcnt(14)
	v_mfma_f32_32x32x16_bf16 v[96:111], v[148:151], v[128:131], v[96:111]
	ds_read_b64_tr_b16 v[6:7], v0 offset:27648
	ds_read_b64_tr_b16 v[8:9], v0 offset:28160
	v_add_f32_e32 v2, v58, v2
	v_add_f32_e32 v2, v59, v2
	v_add_f32_e32 v2, v60, v2
	v_add_f32_e32 v14, v61, v2
	v_cvt_pk_bf16_f32 v112, v56, v57
	v_cvt_pk_bf16_f32 v113, v58, v59
	s_waitcnt lgkmcnt(14)
	v_mfma_f32_32x32x16_bf16 v[80:95], v[152:155], v[120:123], v[80:95]
	ds_read_b64_tr_b16 v[2:3], v0 offset:31744
	ds_read_b64_tr_b16 v[4:5], v0 offset:32256
	v_add_f32_e32 v0, v62, v14
	v_add_f32_e32 v0, v63, v0
	v_add_f32_e32 v0, 0, v0
	v_cvt_pk_bf16_f32 v114, v60, v61
	v_cvt_pk_bf16_f32 v115, v62, v63
	v_mfma_f32_32x32x16_bf16 v[96:111], v[144:147], v[120:123], v[96:111]
	v_lshl_add_u64 v[14:15], v[182:183], 0, s[44:45]
	s_add_i32 s40, s43, s77
	s_mov_b32 s56, m0
	s_mov_b32 m0, s40
	s_nop 0
	global_load_lds_dwordx4 v[14:15], off
	s_mov_b32 m0, s56
	v_lshl_add_u64 v[14:15], v[180:181], 0, s[44:45]
	s_add_i32 s40, s41, s81
	s_mov_b32 s56, m0
	s_mov_b32 m0, s40
	s_nop 0
	global_load_lds_dwordx4 v[14:15], off
	s_mov_b32 m0, s56
	ds_read_b128 v[48:51], v184 offset:96
	ds_read_b128 v[52:55], v184 offset:224
	s_waitcnt lgkmcnt(2)
	v_add_f32_e32 v80, v80, v222
	v_add_f32_e32 v81, v81, v223
	v_add_f32_e32 v82, v82, v224
	v_add_f32_e32 v83, v83, v225
	v_add_f32_e32 v96, v96, v226
	v_add_f32_e32 v97, v97, v227
	v_add_f32_e32 v98, v98, v228
	v_add_f32_e32 v99, v99, v229
	v_add_f32_e32 v84, v84, v230
	v_add_f32_e32 v85, v85, v231
	v_add_f32_e32 v86, v86, v232
	v_add_f32_e32 v87, v87, v233
	v_add_f32_e32 v100, v100, v242
	v_add_f32_e32 v101, v101, v243
	v_add_f32_e32 v102, v102, v244
	v_add_f32_e32 v103, v103, v245
	v_add_f32_e32 v88, v88, v246
	v_add_f32_e32 v89, v89, v247
	v_add_f32_e32 v90, v90, v248
	v_add_f32_e32 v91, v91, v249
	v_add_f32_e32 v104, v104, v250
	v_add_f32_e32 v105, v105, v251
	v_add_f32_e32 v106, v106, v252
	v_add_f32_e32 v107, v107, v253
	s_waitcnt lgkmcnt(1)
	v_add_f32_e32 v92, v92, v48
	v_add_f32_e32 v93, v93, v49
	v_add_f32_e32 v94, v94, v50
	v_add_f32_e32 v95, v95, v51
	s_waitcnt lgkmcnt(0)
	v_add_f32_e32 v108, v108, v52
	v_add_f32_e32 v109, v109, v53
	v_add_f32_e32 v110, v110, v54
	v_add_f32_e32 v111, v111, v55
	s_nop 0
	s_nop 0
	v_sub_f32_e32 v48, v80, v196
	v_sub_f32_e32 v49, v81, v196
	v_sub_f32_e32 v14, v96, v196
	v_sub_f32_e32 v15, v97, v196
	v_sub_f32_e32 v66, v82, v196
	v_sub_f32_e32 v67, v83, v196
	v_sub_f32_e32 v50, v98, v196
	v_sub_f32_e32 v51, v99, v196
	v_max_f32_e32 v64, v48, v49
	v_sub_f32_e32 v68, v84, v196
	v_sub_f32_e32 v69, v85, v196
	v_sub_f32_e32 v70, v86, v196
	v_sub_f32_e32 v71, v87, v196
	v_max3_f32 v65, v66, v67, v15
	v_max3_f32 v64, v64, v14, v50
	v_sub_f32_e32 v52, v100, v196
	v_sub_f32_e32 v53, v101, v196
	v_sub_f32_e32 v54, v102, v196
	v_sub_f32_e32 v55, v103, v196
	v_max3_f32 v64, v64, v51, v68
	v_max3_f32 v65, v65, v70, v71
	v_sub_f32_e32 v72, v88, v196
	v_sub_f32_e32 v73, v89, v196
	v_sub_f32_e32 v74, v90, v196
	v_sub_f32_e32 v75, v91, v196
	v_max3_f32 v64, v64, v69, v52
	v_max3_f32 v65, v65, v54, v55
	v_sub_f32_e32 v56, v104, v196
	v_sub_f32_e32 v57, v105, v196
	v_sub_f32_e32 v58, v106, v196
	v_sub_f32_e32 v59, v107, v196
	v_max3_f32 v64, v64, v53, v72
	v_max3_f32 v65, v65, v74, v75
	v_sub_f32_e32 v76, v92, v196
	v_sub_f32_e32 v77, v93, v196
	v_sub_f32_e32 v78, v94, v196
	v_sub_f32_e32 v79, v95, v196
	v_max3_f32 v64, v64, v73, v56
	v_max3_f32 v65, v65, v58, v59
	v_sub_f32_e32 v60, v108, v196
	v_sub_f32_e32 v61, v109, v196
	v_sub_f32_e32 v62, v110, v196
	v_sub_f32_e32 v63, v111, v196
	v_max3_f32 v64, v64, v57, v76
	v_max3_f32 v65, v65, v78, v79
	v_max3_f32 v64, v64, v77, v60
	v_max3_f32 v65, v65, v62, v63
	v_max3_f32 v64, v64, v61, v65
	v_mov_b32_e32 v65, v64
	s_nop 1
	v_permlane32_swap_b32_e32 v64, v65
	v_max_f32_e32 v65, v65, v65
	v_max_f32_e32 v64, v64, v64
	v_max_f32_e32 v64, v64, v65
	v_cmp_lt_f32_e32 vcc, s88, v64
	s_cmp_lg_u64 vcc, 0
	v_add_f32_e32 v0, v220, v0
	s_cselect_b64 s[56:57], -1, 0
	s_cbranch_vccnz .LBB0_391

; __device__ __forceinline__ void biasf(f32x16&p0,f32x16&p1,const __attribute__((address_space(3))) float*p){
;   #pragma unroll
;   for(int j=0;j<4;++j){ const f32x4a a=*(const __attribute__((address_space(3))) f32x4a*)(p+8*j), b=*(const __attribute__((address_space(3))) f32x4a*)(p+32+8*j);
;     p0[4*j]+=a[0];p0[4*j+1]+=a[1];p0[4*j+2]+=a[2];p0[4*j+3]+=a[3]; p1[4*j]+=b[0];p1[4*j+1]+=b[1];p1[4*j+2]+=b[2];p1[4*j+3]+=b[3];
;     asm volatile("":"+v"(p0),"+v"(p1)); __builtin_amdgcn_sched_barrier(0); }
; }
; __device__ __forceinline__ void biasd(f32x16&p0,f32x16&p1,const __attribute__((address_space(3))) float*lut,int base){
;   #pragma unroll
;   for(int r=0;r<16;++r){ const int d0=base-((r&3)+8*(r>>2)); unsigned i0=(unsigned)d0; i0=i0>127u?127u:i0; unsigned i1=(unsigned)(d0-32); i1=i1>127u?127u:i1; p0[r]+=lut[i0]; p1[r]+=lut[i1];
;     if((r&3)==3){ asm volatile("":"+v"(p0),"+v"(p1)); __builtin_amdgcn_sched_barrier(0); } }
; }
; __device__ __forceinline__ void submh(f32x16&p0,f32x16&p1,float mh){ const f32x2a m2={mh,mh};
;   #pragma unroll
;   for(int r=0;r<16;r+=2){ f32x2a a={p0[r],p0[r+1]}, b={p1[r],p1[r+1]}; a=a-m2; b=b-m2; p0[r]=a[0];p0[r+1]=a[1];p1[r]=b[0];p1[r+1]=b[1]; }
; }
.LBB0_386:
	ds_read_b128 v[222:225], v184 offset:256
	ds_read_b128 v[226:229], v184 offset:384
	ds_read_b128 v[230:233], v184 offset:288
	ds_read_b128 v[242:245], v184 offset:416
	ds_read_b128 v[246:249], v184 offset:320
	ds_read_b128 v[250:253], v184 offset:448
	s_add_i32 s40, s41, 0x2000
	s_cmpk_lg_i32 s41, 0x4000
	s_cselect_b32 s80, s40, 0
	v_add_u32_e32 v4, s43, v219
	ds_read_b64_tr_b16 v[160:161], v4 offset:24576
	ds_read_b64_tr_b16 v[162:163], v4 offset:25088
	v_add_f32_e32 v2, v64, v65
	v_add_f32_e32 v2, v66, v2
	v_add_f32_e32 v2, v67, v2
	v_add_f32_e32 v2, v68, v2
	v_add_f32_e32 v2, v69, v2
	v_cvt_pk_bf16_f32 v132, v64, v65
	v_cvt_pk_bf16_f32 v133, v66, v67
	s_waitcnt lgkmcnt(9)
	v_mfma_f32_32x32x16_bf16 v[80:95], v[80:83], v[140:143], 0
	ds_read_b64_tr_b16 v[156:157], v4 offset:28672
	ds_read_b64_tr_b16 v[158:159], v4 offset:29184
	v_add_f32_e32 v2, v70, v2
	v_add_f32_e32 v2, v71, v2
	v_add_f32_e32 v2, v72, v2
	v_add_f32_e32 v2, v73, v2
	v_cvt_pk_bf16_f32 v134, v68, v69
	v_cvt_pk_bf16_f32 v135, v70, v71
	s_waitcnt lgkmcnt(10)
	v_mfma_f32_32x32x16_bf16 v[96:111], v[96:99], v[140:143], 0
	ds_read_b64_tr_b16 v[152:153], v4 offset:25600
	ds_read_b64_tr_b16 v[154:155], v4 offset:26112
	v_add_f32_e32 v2, v74, v2
	v_add_f32_e32 v2, v75, v2
	v_add_f32_e32 v2, v76, v2
	v_add_f32_e32 v2, v77, v2
	v_cvt_pk_bf16_f32 v124, v72, v73
	v_cvt_pk_bf16_f32 v125, v74, v75
	s_waitcnt lgkmcnt(11)
	v_mfma_f32_32x32x16_bf16 v[80:95], v[148:151], v[136:139], v[80:95]
	ds_read_b64_tr_b16 v[148:149], v4 offset:29696
	ds_read_b64_tr_b16 v[150:151], v4 offset:30208
	v_add_f32_e32 v2, v78, v2
	v_add_f32_e32 v2, v79, v2
	v_add_f32_e32 v2, v48, v2
	v_add_f32_e32 v2, v49, v2
	v_cvt_pk_bf16_f32 v126, v76, v77
	v_cvt_pk_bf16_f32 v127, v78, v79
	s_waitcnt lgkmcnt(12)
	v_mfma_f32_32x32x16_bf16 v[96:111], v[144:147], v[136:139], v[96:111]
	ds_read_b64_tr_b16 v[144:145], v4 offset:26624
	ds_read_b64_tr_b16 v[146:147], v4 offset:27136
	v_add_f32_e32 v2, v50, v2
	v_add_f32_e32 v2, v51, v2
	v_add_f32_e32 v2, v52, v2
	v_add_f32_e32 v2, v53, v2
	v_cvt_pk_bf16_f32 v116, v48, v49
	v_cvt_pk_bf16_f32 v117, v50, v51
	s_waitcnt lgkmcnt(13)
	v_mfma_f32_32x32x16_bf16 v[80:95], v[176:179], v[128:131], v[80:95]
	ds_read_b64_tr_b16 v[10:11], v4 offset:30720
	ds_read_b64_tr_b16 v[12:13], v4 offset:31232
	v_add_f32_e32 v2, v54, v2
	v_add_f32_e32 v2, v55, v2
	v_add_f32_e32 v2, v56, v2
	v_add_f32_e32 v2, v57, v2
	v_cvt_pk_bf16_f32 v118, v52, v53
	v_cvt_pk_bf16_f32 v119, v54, v55
	s_waitcnt lgkmcnt(14)
	v_mfma_f32_32x32x16_bf16 v[96:111], v[168:171], v[128:131], v[96:111]
	ds_read_b64_tr_b16 v[6:7], v4 offset:27648
	ds_read_b64_tr_b16 v[8:9], v4 offset:28160
	v_add_f32_e32 v2, v58, v2
	v_add_f32_e32 v2, v59, v2
	v_add_f32_e32 v2, v60, v2
	v_add_f32_e32 v14, v61, v2
	v_cvt_pk_bf16_f32 v112, v56, v57
	v_cvt_pk_bf16_f32 v113, v58, v59
	s_waitcnt lgkmcnt(14)
	v_mfma_f32_32x32x16_bf16 v[80:95], v[172:175], v[120:123], v[80:95]
	ds_read_b64_tr_b16 v[2:3], v4 offset:31744
	ds_read_b64_tr_b16 v[4:5], v4 offset:32256
	v_add_f32_e32 v14, v62, v14
	v_add_f32_e32 v14, v63, v14
	v_add_f32_e32 v64, 0, v14
	v_cvt_pk_bf16_f32 v114, v60, v61
	v_cvt_pk_bf16_f32 v115, v62, v63
	v_mfma_f32_32x32x16_bf16 v[96:111], v[164:167], v[120:123], v[96:111]
	s_add_i32 s40, s41, s77
	s_mov_b32 s43, m0
	s_mov_b32 m0, s40
	s_nop 0
	global_load_lds_dwordx4 v[182:183], off
	s_mov_b32 m0, s43
	s_add_i32 s40, s80, s81
	s_mov_b32 s43, m0
	s_mov_b32 m0, s40
	s_nop 0
	global_load_lds_dwordx4 v[180:181], off
	s_mov_b32 m0, s43
	ds_read_b128 v[48:51], v184 offset:352
	ds_read_b128 v[52:55], v184 offset:480
	s_waitcnt lgkmcnt(2)
	v_add_f32_e32 v80, v80, v222
	v_add_f32_e32 v81, v81, v223
	v_add_f32_e32 v82, v82, v224
	v_add_f32_e32 v83, v83, v225
	v_add_f32_e32 v96, v96, v226
	v_add_f32_e32 v97, v97, v227
	v_add_f32_e32 v98, v98, v228
	v_add_f32_e32 v99, v99, v229
	v_add_f32_e32 v84, v84, v230
	v_add_f32_e32 v85, v85, v231
	v_add_f32_e32 v86, v86, v232
	v_add_f32_e32 v87, v87, v233
	v_add_f32_e32 v100, v100, v242
	v_add_f32_e32 v101, v101, v243
	v_add_f32_e32 v102, v102, v244
	v_add_f32_e32 v103, v103, v245
	v_add_f32_e32 v88, v88, v246
	v_add_f32_e32 v89, v89, v247
	v_add_f32_e32 v90, v90, v248
	v_add_f32_e32 v91, v91, v249
	v_add_f32_e32 v104, v104, v250
	v_add_f32_e32 v105, v105, v251
	v_add_f32_e32 v106, v106, v252
	v_add_f32_e32 v107, v107, v253
	s_waitcnt lgkmcnt(1)
	v_add_f32_e32 v92, v92, v48
	v_add_f32_e32 v93, v93, v49
	v_add_f32_e32 v94, v94, v50
	v_add_f32_e32 v95, v95, v51
	s_waitcnt lgkmcnt(0)
	v_add_f32_e32 v108, v108, v52
	v_add_f32_e32 v109, v109, v53
	v_add_f32_e32 v110, v110, v54
	v_add_f32_e32 v111, v111, v55
	s_nop 0
	s_nop 0
	v_sub_f32_e32 v48, v80, v196
	v_sub_f32_e32 v49, v81, v196
	v_sub_f32_e32 v14, v96, v196
	v_sub_f32_e32 v15, v97, v196
	v_sub_f32_e32 v66, v82, v196
	v_sub_f32_e32 v67, v83, v196
	v_sub_f32_e32 v50, v98, v196
	v_sub_f32_e32 v51, v99, v196
	v_max_f32_e32 v65, v48, v49
	v_sub_f32_e32 v68, v84, v196
	v_sub_f32_e32 v69, v85, v196
	v_sub_f32_e32 v70, v86, v196
	v_sub_f32_e32 v71, v87, v196
	v_max3_f32 v80, v66, v67, v15
	v_max3_f32 v65, v65, v14, v50
	v_sub_f32_e32 v52, v100, v196
	v_sub_f32_e32 v53, v101, v196
	v_sub_f32_e32 v54, v102, v196
	v_sub_f32_e32 v55, v103, v196
	v_max3_f32 v65, v65, v51, v68
	v_max3_f32 v80, v80, v70, v71
	v_sub_f32_e32 v72, v88, v196
	v_sub_f32_e32 v73, v89, v196
	v_sub_f32_e32 v74, v90, v196
	v_sub_f32_e32 v75, v91, v196
	v_max3_f32 v65, v65, v69, v52
	v_max3_f32 v80, v80, v54, v55
	v_sub_f32_e32 v56, v104, v196
	v_sub_f32_e32 v57, v105, v196
	v_sub_f32_e32 v58, v106, v196
	v_sub_f32_e32 v59, v107, v196
	v_max3_f32 v65, v65, v53, v72
	v_max3_f32 v80, v80, v74, v75
	v_sub_f32_e32 v76, v92, v196
	v_sub_f32_e32 v77, v93, v196
	v_sub_f32_e32 v78, v94, v196
	v_sub_f32_e32 v79, v95, v196
	v_max3_f32 v65, v65, v73, v56
	v_max3_f32 v80, v80, v58, v59
	v_sub_f32_e32 v60, v108, v196
	v_sub_f32_e32 v61, v109, v196
	v_sub_f32_e32 v62, v110, v196
	v_sub_f32_e32 v63, v111, v196
	v_max3_f32 v65, v65, v57, v76
	v_max3_f32 v80, v80, v78, v79
	v_max3_f32 v65, v65, v77, v60
	v_max3_f32 v80, v80, v62, v63
	v_add_f32_e32 v220, v0, v64
	v_max3_f32 v0, v65, v61, v80
	v_mov_b32_e32 v64, v0
	s_nop 1
	v_permlane32_swap_b32_e32 v0, v64
	v_max_f32_e32 v64, v64, v64
	v_max_f32_e32 v0, v0, v0
	v_max_f32_e32 v0, v0, v64
	v_cmp_lt_f32_e32 vcc, s88, v0
	s_cmp_lg_u64 vcc, 0
	s_cselect_b64 s[56:57], -1, 0
	s_cbranch_vccnz .LBB0_394

; __device__ __forceinline__ void submh(f32x16&p0,f32x16&p1,float mh){ const f32x2a m2={mh,mh};
;   #pragma unroll
;   for(int r=0;r<16;r+=2){ f32x2a a={p0[r],p0[r+1]}, b={p1[r],p1[r+1]}; a=a-m2; b=b-m2; p0[r]=a[0];p0[r+1]=a[1];p1[r]=b[0];p1[r+1]=b[1]; }
; }
.LBB0_469:
	s_lshl_b32 s6, s6, 1
	v_add_u32_e32 v212, s6, v250
	ds_read_b64_tr_b16 v[208:209], v212 offset:24576
	ds_read_b64_tr_b16 v[210:211], v212 offset:25088
	v_add_f32_e32 v0, v96, v97
	v_add_f32_e32 v0, v98, v0
	v_add_f32_e32 v0, v99, v0
	v_add_f32_e32 v0, v100, v0
	v_add_f32_e32 v0, v101, v0
	v_cvt_pk_bf16_f32 v156, v96, v97
	v_cvt_pk_bf16_f32 v157, v98, v99
	v_mfma_f32_32x32x16_bf16 v[112:127], v[204:207], v[172:175], 0
	ds_read_b64_tr_b16 v[204:205], v212 offset:28672
	ds_read_b64_tr_b16 v[206:207], v212 offset:29184
	v_add_f32_e32 v0, v102, v0
	v_add_f32_e32 v0, v103, v0
	v_add_f32_e32 v0, v104, v0
	v_add_f32_e32 v0, v105, v0
	v_cvt_pk_bf16_f32 v158, v100, v101
	v_cvt_pk_bf16_f32 v159, v102, v103
	v_mfma_f32_32x32x16_bf16 v[128:143], v[200:203], v[172:175], 0
	ds_read_b64_tr_b16 v[10:11], v212 offset:25600
	ds_read_b64_tr_b16 v[12:13], v212 offset:26112
	v_add_f32_e32 v0, v106, v0
	v_add_f32_e32 v0, v107, v0
	v_add_f32_e32 v0, v108, v0
	v_add_f32_e32 v0, v109, v0
	v_cvt_pk_bf16_f32 v152, v104, v105
	v_cvt_pk_bf16_f32 v153, v106, v107
	v_mfma_f32_32x32x16_bf16 v[112:127], v[196:199], v[168:171], v[112:127]
	ds_read_b64_tr_b16 v[6:7], v212 offset:29696
	ds_read_b64_tr_b16 v[8:9], v212 offset:30208
	v_add_f32_e32 v0, v110, v0
	v_add_f32_e32 v0, v111, v0
	v_add_f32_e32 v0, v80, v0
	v_add_f32_e32 v0, v81, v0
	v_cvt_pk_bf16_f32 v154, v108, v109
	v_cvt_pk_bf16_f32 v155, v110, v111
	v_mfma_f32_32x32x16_bf16 v[128:143], v[192:195], v[168:171], v[128:143]
	ds_read_b64_tr_b16 v[2:3], v212 offset:26624
	ds_read_b64_tr_b16 v[4:5], v212 offset:27136
	v_add_f32_e32 v0, v82, v0
	v_add_f32_e32 v0, v83, v0
	v_add_f32_e32 v0, v84, v0
	v_add_f32_e32 v0, v85, v0
	v_cvt_pk_bf16_f32 v148, v80, v81
	v_cvt_pk_bf16_f32 v149, v82, v83
	v_mfma_f32_32x32x16_bf16 v[112:127], v[188:191], v[164:167], v[112:127]
	ds_read_b64_tr_b16 v[188:189], v212 offset:30720
	ds_read_b64_tr_b16 v[190:191], v212 offset:31232
	v_add_f32_e32 v0, v86, v0
	v_add_f32_e32 v0, v87, v0
	v_add_f32_e32 v0, v88, v0
	v_add_f32_e32 v0, v89, v0
	v_cvt_pk_bf16_f32 v150, v84, v85
	v_cvt_pk_bf16_f32 v151, v86, v87
	v_mfma_f32_32x32x16_bf16 v[128:143], v[184:187], v[164:167], v[128:143]
	ds_read_b64_tr_b16 v[192:193], v212 offset:27648
	ds_read_b64_tr_b16 v[194:195], v212 offset:28160
	v_add_f32_e32 v0, v90, v0
	v_add_f32_e32 v0, v91, v0
	v_add_f32_e32 v0, v92, v0
	v_add_f32_e32 v0, v93, v0
	v_cvt_pk_bf16_f32 v144, v88, v89
	v_cvt_pk_bf16_f32 v145, v90, v91
	v_mfma_f32_32x32x16_bf16 v[112:127], v[180:183], v[160:163], v[112:127]
	ds_read_b64_tr_b16 v[196:197], v212 offset:31744
	ds_read_b64_tr_b16 v[198:199], v212 offset:32256
	v_add_f32_e32 v0, v94, v0
	v_add_f32_e32 v0, v95, v0
	v_add_f32_e32 v0, 0, v0
	v_cvt_pk_bf16_f32 v146, v92, v93
	v_cvt_pk_bf16_f32 v147, v94, v95
	v_mfma_f32_32x32x16_bf16 v[128:143], v[176:179], v[160:163], v[128:143]
	s_lshl_b32 s41, s42, 13
	s_add_i32 s7, s48, s77
	s_mov_b32 m0, s7
	s_add_i32 s6, s41, 0x6000
	buffer_load_dwordx4 v247, s[12:15], s6 offen lds
	s_lshl_b32 s7, s40, 1
	s_add_i32 s6, s43, 0x4000
	s_add_i32 s44, s7, s81
	s_mov_b32 m0, s44
	s_nop 0
	buffer_load_dwordx4 v248, s[16:19], s6 offen lds
	s_add_i32 s6, s43, 0x4080
	s_add_i32 s7, s7, s55
	s_mov_b32 m0, s7
	s_nop 0
	buffer_load_dwordx4 v248, s[16:19], s6 offen lds
	v_add_f32_e64 v80, v112, -v228
	v_add_f32_e64 v81, v113, -v228
	v_sub_f32_e32 v14, v128, v228
	v_sub_f32_e32 v15, v129, v228
	v_sub_f32_e32 v98, v114, v228
	v_sub_f32_e32 v99, v115, v228
	v_sub_f32_e32 v82, v130, v228
	v_sub_f32_e32 v83, v131, v228
	v_max_f32_e32 v96, v80, v81
	v_sub_f32_e32 v100, v116, v228
	v_sub_f32_e32 v101, v117, v228
	v_sub_f32_e32 v102, v118, v228
	v_sub_f32_e32 v103, v119, v228
	v_max3_f32 v97, v98, v99, v15
	v_max3_f32 v96, v96, v14, v82
	v_sub_f32_e32 v84, v132, v228
	v_sub_f32_e32 v85, v133, v228
	v_sub_f32_e32 v86, v134, v228
	v_sub_f32_e32 v87, v135, v228
	v_max3_f32 v96, v96, v83, v100
	v_max3_f32 v97, v97, v102, v103
	v_sub_f32_e32 v104, v120, v228
	v_sub_f32_e32 v105, v121, v228
	v_sub_f32_e32 v106, v122, v228
	v_sub_f32_e32 v107, v123, v228
	v_max3_f32 v96, v96, v101, v84
	v_max3_f32 v97, v97, v86, v87
	v_sub_f32_e32 v88, v136, v228
	v_sub_f32_e32 v89, v137, v228
	v_sub_f32_e32 v90, v138, v228
	v_sub_f32_e32 v91, v139, v228
	v_max3_f32 v96, v96, v85, v104
	v_max3_f32 v97, v97, v106, v107
	v_sub_f32_e32 v108, v124, v228
	v_sub_f32_e32 v109, v125, v228
	v_sub_f32_e32 v110, v126, v228
	v_sub_f32_e32 v111, v127, v228
	v_max3_f32 v96, v96, v105, v88
	v_max3_f32 v97, v97, v90, v91
	v_sub_f32_e32 v92, v140, v228
	v_sub_f32_e32 v93, v141, v228
	v_sub_f32_e32 v94, v142, v228
	v_sub_f32_e32 v95, v143, v228
	v_max3_f32 v96, v96, v89, v108
	v_max3_f32 v97, v97, v110, v111
	v_max3_f32 v96, v96, v109, v92
	v_max3_f32 v97, v97, v94, v95
	v_max3_f32 v96, v96, v93, v97
	v_add_f32_e32 v0, v251, v0
	v_cmp_lt_f32_e32 vcc, s83, v96
	s_cmp_lg_u64 vcc, 0
	s_cselect_b64 s[6:7], -1, 0
	s_cbranch_vccnz .LBB0_477

; __device__ __forceinline__ void submh(f32x16&p0,f32x16&p1,float mh){ const f32x2a m2={mh,mh};
;   #pragma unroll
;   for(int r=0;r<16;r+=2){ f32x2a a={p0[r],p0[r+1]}, b={p1[r],p1[r+1]}; a=a-m2; b=b-m2; p0[r]=a[0];p0[r+1]=a[1];p1[r]=b[0];p1[r+1]=b[1]; }
; }
.LBB0_472:
	s_add_i32 s6, s40, 0x2000
	s_cmpk_lg_i32 s40, 0x4000
	s_cselect_b32 s91, s6, 0
	s_lshl_b32 s6, s48, 1
	v_add_u32_e32 v14, s6, v250
	ds_read_b64_tr_b16 v[192:193], v14 offset:24576
	ds_read_b64_tr_b16 v[194:195], v14 offset:25088
	v_add_f32_e32 v15, v96, v97
	v_add_f32_e32 v15, v98, v15
	v_add_f32_e32 v15, v99, v15
	v_add_f32_e32 v15, v100, v15
	v_add_f32_e32 v15, v101, v15
	v_cvt_pk_bf16_f32 v156, v96, v97
	v_cvt_pk_bf16_f32 v157, v98, v99
	v_mfma_f32_32x32x16_bf16 v[112:127], v[112:115], v[172:175], 0
	ds_read_b64_tr_b16 v[196:197], v14 offset:28672
	ds_read_b64_tr_b16 v[198:199], v14 offset:29184
	v_add_f32_e32 v15, v102, v15
	v_add_f32_e32 v15, v103, v15
	v_add_f32_e32 v15, v104, v15
	v_add_f32_e32 v15, v105, v15
	v_cvt_pk_bf16_f32 v158, v100, v101
	v_cvt_pk_bf16_f32 v159, v102, v103
	v_mfma_f32_32x32x16_bf16 v[128:143], v[128:131], v[172:175], 0
	ds_read_b64_tr_b16 v[188:189], v14 offset:25600
	ds_read_b64_tr_b16 v[190:191], v14 offset:26112
	v_add_f32_e32 v15, v106, v15
	v_add_f32_e32 v15, v107, v15
	v_add_f32_e32 v15, v108, v15
	v_add_f32_e32 v15, v109, v15
	v_cvt_pk_bf16_f32 v152, v104, v105
	v_cvt_pk_bf16_f32 v153, v106, v107
	v_mfma_f32_32x32x16_bf16 v[112:127], v[184:187], v[168:171], v[112:127]
	ds_read_b64_tr_b16 v[184:185], v14 offset:29696
	ds_read_b64_tr_b16 v[186:187], v14 offset:30208
	v_add_f32_e32 v15, v110, v15
	v_add_f32_e32 v15, v111, v15
	v_add_f32_e32 v15, v80, v15
	v_add_f32_e32 v15, v81, v15
	v_cvt_pk_bf16_f32 v154, v108, v109
	v_cvt_pk_bf16_f32 v155, v110, v111
	v_mfma_f32_32x32x16_bf16 v[128:143], v[176:179], v[168:171], v[128:143]
	ds_read_b64_tr_b16 v[176:177], v14 offset:26624
	ds_read_b64_tr_b16 v[178:179], v14 offset:27136
	v_add_f32_e32 v15, v82, v15
	v_add_f32_e32 v15, v83, v15
	v_add_f32_e32 v15, v84, v15
	v_add_f32_e32 v15, v85, v15
	v_cvt_pk_bf16_f32 v148, v80, v81
	v_cvt_pk_bf16_f32 v149, v82, v83
	v_mfma_f32_32x32x16_bf16 v[112:127], v[180:183], v[164:167], v[112:127]
	ds_read_b64_tr_b16 v[208:209], v14 offset:30720
	ds_read_b64_tr_b16 v[210:211], v14 offset:31232
	v_add_f32_e32 v15, v86, v15
	v_add_f32_e32 v15, v87, v15
	v_add_f32_e32 v15, v88, v15
	v_add_f32_e32 v15, v89, v15
	v_cvt_pk_bf16_f32 v150, v84, v85
	v_cvt_pk_bf16_f32 v151, v86, v87
	v_mfma_f32_32x32x16_bf16 v[128:143], v[6:9], v[164:167], v[128:143]
	ds_read_b64_tr_b16 v[6:7], v14 offset:27648
	ds_read_b64_tr_b16 v[8:9], v14 offset:28160
	v_add_f32_e32 v15, v90, v15
	v_add_f32_e32 v15, v91, v15
	v_add_f32_e32 v15, v92, v15
	v_add_f32_e32 v15, v93, v15
	v_cvt_pk_bf16_f32 v144, v88, v89
	v_cvt_pk_bf16_f32 v145, v90, v91
	v_mfma_f32_32x32x16_bf16 v[112:127], v[10:13], v[160:163], v[112:127]
	ds_read_b64_tr_b16 v[10:11], v14 offset:31744
	ds_read_b64_tr_b16 v[12:13], v14 offset:32256
	v_add_f32_e32 v15, v94, v15
	v_add_f32_e32 v15, v95, v15
	v_add_f32_e32 v15, 0, v15
	v_cvt_pk_bf16_f32 v146, v92, v93
	v_cvt_pk_bf16_f32 v147, v94, v95
	v_mfma_f32_32x32x16_bf16 v[128:143], v[2:5], v[160:163], v[128:143]
	s_add_i32 s6, s40, s77
	s_mov_b32 m0, s6
	s_add_i32 s41, s41, 0x8000
	buffer_load_dwordx4 v247, s[12:15], s41 offen lds
	s_lshl_b32 s6, s91, 1
	s_add_i32 s48, s43, 0x8000
	s_add_i32 s7, s6, s81
	s_mov_b32 m0, s7
	s_nop 0
	buffer_load_dwordx4 v248, s[16:19], s48 offen lds
	s_add_i32 s7, s43, 0x8080
	s_add_i32 s6, s6, s55
	s_mov_b32 m0, s6
	s_nop 0
	buffer_load_dwordx4 v248, s[16:19], s7 offen lds
	v_add_f32_e64 v4, v112, -v228
	v_add_f32_e64 v5, v113, -v228
	v_sub_f32_e32 v2, v128, v228
	v_sub_f32_e32 v3, v129, v228
	v_sub_f32_e32 v98, v114, v228
	v_sub_f32_e32 v99, v115, v228
	v_sub_f32_e32 v82, v130, v228
	v_sub_f32_e32 v83, v131, v228
	v_max_f32_e32 v80, v4, v5
	v_sub_f32_e32 v100, v116, v228
	v_sub_f32_e32 v101, v117, v228
	v_sub_f32_e32 v102, v118, v228
	v_sub_f32_e32 v103, v119, v228
	v_max3_f32 v81, v98, v99, v3
	v_max3_f32 v80, v80, v2, v82
	v_sub_f32_e32 v84, v132, v228
	v_sub_f32_e32 v85, v133, v228
	v_sub_f32_e32 v86, v134, v228
	v_sub_f32_e32 v87, v135, v228
	v_max3_f32 v80, v80, v83, v100
	v_max3_f32 v81, v81, v102, v103
	v_sub_f32_e32 v104, v120, v228
	v_sub_f32_e32 v105, v121, v228
	v_sub_f32_e32 v106, v122, v228
	v_sub_f32_e32 v107, v123, v228
	v_max3_f32 v80, v80, v101, v84
	v_max3_f32 v81, v81, v86, v87
	v_sub_f32_e32 v88, v136, v228
	v_sub_f32_e32 v89, v137, v228
	v_sub_f32_e32 v90, v138, v228
	v_sub_f32_e32 v91, v139, v228
	v_max3_f32 v80, v80, v85, v104
	v_max3_f32 v81, v81, v106, v107
	v_sub_f32_e32 v108, v124, v228
	v_sub_f32_e32 v109, v125, v228
	v_sub_f32_e32 v110, v126, v228
	v_sub_f32_e32 v111, v127, v228
	v_max3_f32 v80, v80, v105, v88
	v_max3_f32 v81, v81, v90, v91
	v_sub_f32_e32 v92, v140, v228
	v_sub_f32_e32 v93, v141, v228
	v_sub_f32_e32 v94, v142, v228
	v_sub_f32_e32 v95, v143, v228
	v_max3_f32 v80, v80, v89, v108
	v_max3_f32 v81, v81, v110, v111
	v_max3_f32 v80, v80, v109, v92
	v_max3_f32 v81, v81, v94, v95
	v_add_f32_e32 v251, v0, v15
	v_max3_f32 v0, v80, v93, v81
	v_cmp_lt_f32_e32 vcc, s83, v0
	s_cmp_lg_u64 vcc, 0
	s_cselect_b64 s[6:7], -1, 0
	s_cbranch_vccnz .LBB0_480

; __device__ __forceinline__ void biasf(f32x16&p0,f32x16&p1,const __attribute__((address_space(3))) float*p){
;   #pragma unroll
;   for(int j=0;j<4;++j){ const f32x4a a=*(const __attribute__((address_space(3))) f32x4a*)(p+8*j), b=*(const __attribute__((address_space(3))) f32x4a*)(p+32+8*j);
;     p0[4*j]+=a[0];p0[4*j+1]+=a[1];p0[4*j+2]+=a[2];p0[4*j+3]+=a[3]; p1[4*j]+=b[0];p1[4*j+1]+=b[1];p1[4*j+2]+=b[2];p1[4*j+3]+=b[3];
;     asm volatile("":"+v"(p0),"+v"(p1)); __builtin_amdgcn_sched_barrier(0); }
; }
; __device__ __forceinline__ void biasd(f32x16&p0,f32x16&p1,const __attribute__((address_space(3))) float*lut,int base){
;   #pragma unroll
;   for(int r=0;r<16;++r){ const int d0=base-((r&3)+8*(r>>2)); unsigned i0=(unsigned)d0; i0=i0>127u?127u:i0; unsigned i1=(unsigned)(d0-32); i1=i1>127u?127u:i1; p0[r]+=lut[i0]; p1[r]+=lut[i1];
;     if((r&3)==3){ asm volatile("":"+v"(p0),"+v"(p1)); __builtin_amdgcn_sched_barrier(0); } }
; }
; __device__ __forceinline__ void submh(f32x16&p0,f32x16&p1,float mh){ const f32x2a m2={mh,mh};
;   #pragma unroll
;   for(int r=0;r<16;r+=2){ f32x2a a={p0[r],p0[r+1]}, b={p1[r],p1[r+1]}; a=a-m2; b=b-m2; p0[r]=a[0];p0[r+1]=a[1];p1[r]=b[0];p1[r+1]=b[1]; }
; }
.LBB0_1423:
	ds_read_b128 v[222:225], v184
	ds_read_b128 v[226:229], v184 offset:128
	ds_read_b128 v[230:233], v184 offset:32
	ds_read_b128 v[242:245], v184 offset:160
	ds_read_b128 v[246:249], v184 offset:64
	ds_read_b128 v[250:253], v184 offset:192
	v_add_u32_e32 v0, s54, v219
	ds_read_b64_tr_b16 v[176:177], v0 offset:24576
	ds_read_b64_tr_b16 v[178:179], v0 offset:25088
	v_add_f32_e32 v2, v64, v65
	v_add_f32_e32 v2, v66, v2
	v_add_f32_e32 v2, v67, v2
	v_add_f32_e32 v2, v68, v2
	v_add_f32_e32 v2, v69, v2
	v_cvt_pk_bf16_f32 v132, v64, v65
	v_cvt_pk_bf16_f32 v133, v66, v67
	s_waitcnt lgkmcnt(9)
	v_mfma_f32_32x32x16_bf16 v[80:95], v[172:175], v[140:143], 0
	ds_read_b64_tr_b16 v[172:173], v0 offset:28672
	ds_read_b64_tr_b16 v[174:175], v0 offset:29184
	v_add_f32_e32 v2, v70, v2
	v_add_f32_e32 v2, v71, v2
	v_add_f32_e32 v2, v72, v2
	v_add_f32_e32 v2, v73, v2
	v_cvt_pk_bf16_f32 v134, v68, v69
	v_cvt_pk_bf16_f32 v135, v70, v71
	s_waitcnt lgkmcnt(10)
	v_mfma_f32_32x32x16_bf16 v[96:111], v[168:171], v[140:143], 0
	ds_read_b64_tr_b16 v[168:169], v0 offset:25600
	ds_read_b64_tr_b16 v[170:171], v0 offset:26112
	v_add_f32_e32 v2, v74, v2
	v_add_f32_e32 v2, v75, v2
	v_add_f32_e32 v2, v76, v2
	v_add_f32_e32 v2, v77, v2
	v_cvt_pk_bf16_f32 v124, v72, v73
	v_cvt_pk_bf16_f32 v125, v74, v75
	s_waitcnt lgkmcnt(11)
	v_mfma_f32_32x32x16_bf16 v[80:95], v[164:167], v[136:139], v[80:95]
	ds_read_b64_tr_b16 v[164:165], v0 offset:29696
	ds_read_b64_tr_b16 v[166:167], v0 offset:30208
	v_add_f32_e32 v2, v78, v2
	v_add_f32_e32 v2, v79, v2
	v_add_f32_e32 v2, v48, v2
	v_add_f32_e32 v2, v49, v2
	v_cvt_pk_bf16_f32 v126, v76, v77
	v_cvt_pk_bf16_f32 v127, v78, v79
	s_waitcnt lgkmcnt(12)
	v_mfma_f32_32x32x16_bf16 v[96:111], v[160:163], v[136:139], v[96:111]
	ds_read_b64_tr_b16 v[160:161], v0 offset:26624
	ds_read_b64_tr_b16 v[162:163], v0 offset:27136
	v_add_f32_e32 v2, v50, v2
	v_add_f32_e32 v2, v51, v2
	v_add_f32_e32 v2, v52, v2
	v_add_f32_e32 v2, v53, v2
	v_cvt_pk_bf16_f32 v116, v48, v49
	v_cvt_pk_bf16_f32 v117, v50, v51
	s_waitcnt lgkmcnt(13)
	v_mfma_f32_32x32x16_bf16 v[80:95], v[156:159], v[128:131], v[80:95]
	ds_read_b64_tr_b16 v[10:11], v0 offset:30720
	ds_read_b64_tr_b16 v[12:13], v0 offset:31232
	v_add_f32_e32 v2, v54, v2
	v_add_f32_e32 v2, v55, v2
	v_add_f32_e32 v2, v56, v2
	v_add_f32_e32 v2, v57, v2
	v_cvt_pk_bf16_f32 v118, v52, v53
	v_cvt_pk_bf16_f32 v119, v54, v55
	s_waitcnt lgkmcnt(14)
	v_mfma_f32_32x32x16_bf16 v[96:111], v[148:151], v[128:131], v[96:111]
	ds_read_b64_tr_b16 v[6:7], v0 offset:27648
	ds_read_b64_tr_b16 v[8:9], v0 offset:28160
	v_add_f32_e32 v2, v58, v2
	v_add_f32_e32 v2, v59, v2
	v_add_f32_e32 v2, v60, v2
	v_add_f32_e32 v14, v61, v2
	v_cvt_pk_bf16_f32 v112, v56, v57
	v_cvt_pk_bf16_f32 v113, v58, v59
	s_waitcnt lgkmcnt(14)
	v_mfma_f32_32x32x16_bf16 v[80:95], v[152:155], v[120:123], v[80:95]
	ds_read_b64_tr_b16 v[2:3], v0 offset:31744
	ds_read_b64_tr_b16 v[4:5], v0 offset:32256
	v_add_f32_e32 v0, v62, v14
	v_add_f32_e32 v0, v63, v0
	v_add_f32_e32 v0, 0, v0
	v_cvt_pk_bf16_f32 v114, v60, v61
	v_cvt_pk_bf16_f32 v115, v62, v63
	v_mfma_f32_32x32x16_bf16 v[96:111], v[144:147], v[120:123], v[96:111]
	v_lshl_add_u64 v[14:15], v[182:183], 0, s[42:43]
	s_add_i32 s54, s97, s66
	s_mov_b32 s55, m0
	s_mov_b32 m0, s54
	s_nop 0
	global_load_lds_dwordx4 v[14:15], off
	s_mov_b32 m0, s55
	v_lshl_add_u64 v[14:15], v[180:181], 0, s[42:43]
	s_add_i32 s54, s62, s67
	s_mov_b32 s55, m0
	s_mov_b32 m0, s54
	s_nop 0
	global_load_lds_dwordx4 v[14:15], off
	s_mov_b32 m0, s55
	ds_read_b128 v[48:51], v184 offset:96
	ds_read_b128 v[52:55], v184 offset:224
	s_waitcnt lgkmcnt(2)
	v_add_f32_e32 v80, v80, v222
	v_add_f32_e32 v81, v81, v223
	v_add_f32_e32 v82, v82, v224
	v_add_f32_e32 v83, v83, v225
	v_add_f32_e32 v96, v96, v226
	v_add_f32_e32 v97, v97, v227
	v_add_f32_e32 v98, v98, v228
	v_add_f32_e32 v99, v99, v229
	v_add_f32_e32 v84, v84, v230
	v_add_f32_e32 v85, v85, v231
	v_add_f32_e32 v86, v86, v232
	v_add_f32_e32 v87, v87, v233
	v_add_f32_e32 v100, v100, v242
	v_add_f32_e32 v101, v101, v243
	v_add_f32_e32 v102, v102, v244
	v_add_f32_e32 v103, v103, v245
	v_add_f32_e32 v88, v88, v246
	v_add_f32_e32 v89, v89, v247
	v_add_f32_e32 v90, v90, v248
	v_add_f32_e32 v91, v91, v249
	v_add_f32_e32 v104, v104, v250
	v_add_f32_e32 v105, v105, v251
	v_add_f32_e32 v106, v106, v252
	v_add_f32_e32 v107, v107, v253
	s_waitcnt lgkmcnt(1)
	v_add_f32_e32 v92, v92, v48
	v_add_f32_e32 v93, v93, v49
	v_add_f32_e32 v94, v94, v50
	v_add_f32_e32 v95, v95, v51
	s_waitcnt lgkmcnt(0)
	v_add_f32_e32 v108, v108, v52
	v_add_f32_e32 v109, v109, v53
	v_add_f32_e32 v110, v110, v54
	v_add_f32_e32 v111, v111, v55
	s_nop 0
	s_nop 0
	v_sub_f32_e32 v48, v80, v196
	v_sub_f32_e32 v49, v81, v196
	v_sub_f32_e32 v14, v96, v196
	v_sub_f32_e32 v15, v97, v196
	v_sub_f32_e32 v66, v82, v196
	v_sub_f32_e32 v67, v83, v196
	v_sub_f32_e32 v50, v98, v196
	v_sub_f32_e32 v51, v99, v196
	v_max_f32_e32 v64, v48, v49
	v_sub_f32_e32 v68, v84, v196
	v_sub_f32_e32 v69, v85, v196
	v_sub_f32_e32 v70, v86, v196
	v_sub_f32_e32 v71, v87, v196
	v_max3_f32 v65, v66, v67, v15
	v_max3_f32 v64, v64, v14, v50
	v_sub_f32_e32 v52, v100, v196
	v_sub_f32_e32 v53, v101, v196
	v_sub_f32_e32 v54, v102, v196
	v_sub_f32_e32 v55, v103, v196
	v_max3_f32 v64, v64, v51, v68
	v_max3_f32 v65, v65, v70, v71
	v_sub_f32_e32 v72, v88, v196
	v_sub_f32_e32 v73, v89, v196
	v_sub_f32_e32 v74, v90, v196
	v_sub_f32_e32 v75, v91, v196
	v_max3_f32 v64, v64, v69, v52
	v_max3_f32 v65, v65, v54, v55
	v_sub_f32_e32 v56, v104, v196
	v_sub_f32_e32 v57, v105, v196
	v_sub_f32_e32 v58, v106, v196
	v_sub_f32_e32 v59, v107, v196
	v_max3_f32 v64, v64, v53, v72
	v_max3_f32 v65, v65, v74, v75
	v_sub_f32_e32 v76, v92, v196
	v_sub_f32_e32 v77, v93, v196
	v_sub_f32_e32 v78, v94, v196
	v_sub_f32_e32 v79, v95, v196
	v_max3_f32 v64, v64, v73, v56
	v_max3_f32 v65, v65, v58, v59
	v_sub_f32_e32 v60, v108, v196
	v_sub_f32_e32 v61, v109, v196
	v_sub_f32_e32 v62, v110, v196
	v_sub_f32_e32 v63, v111, v196
	v_max3_f32 v64, v64, v57, v76
	v_max3_f32 v65, v65, v78, v79
	v_max3_f32 v64, v64, v77, v60
	v_max3_f32 v65, v65, v62, v63
	v_max3_f32 v64, v64, v61, v65
	v_mov_b32_e32 v65, v64
	s_nop 1
	v_permlane32_swap_b32_e32 v64, v65
	v_max_f32_e32 v65, v65, v65
	v_max_f32_e32 v64, v64, v64
	v_max_f32_e32 v64, v64, v65
	v_cmp_lt_f32_e32 vcc, s85, v64
	s_cmp_lg_u64 vcc, 0
	v_add_f32_e32 v0, v220, v0
	s_cselect_b64 s[54:55], -1, 0
	s_cbranch_vccnz .LBB0_1431

; __device__ __forceinline__ void biasf(f32x16&p0,f32x16&p1,const __attribute__((address_space(3))) float*p){
;   #pragma unroll
;   for(int j=0;j<4;++j){ const f32x4a a=*(const __attribute__((address_space(3))) f32x4a*)(p+8*j), b=*(const __attribute__((address_space(3))) f32x4a*)(p+32+8*j);
;     p0[4*j]+=a[0];p0[4*j+1]+=a[1];p0[4*j+2]+=a[2];p0[4*j+3]+=a[3]; p1[4*j]+=b[0];p1[4*j+1]+=b[1];p1[4*j+2]+=b[2];p1[4*j+3]+=b[3];
;     asm volatile("":"+v"(p0),"+v"(p1)); __builtin_amdgcn_sched_barrier(0); }
; }
; __device__ __forceinline__ void biasd(f32x16&p0,f32x16&p1,const __attribute__((address_space(3))) float*lut,int base){
;   #pragma unroll
;   for(int r=0;r<16;++r){ const int d0=base-((r&3)+8*(r>>2)); unsigned i0=(unsigned)d0; i0=i0>127u?127u:i0; unsigned i1=(unsigned)(d0-32); i1=i1>127u?127u:i1; p0[r]+=lut[i0]; p1[r]+=lut[i1];
;     if((r&3)==3){ asm volatile("":"+v"(p0),"+v"(p1)); __builtin_amdgcn_sched_barrier(0); } }
; }
; __device__ __forceinline__ void submh(f32x16&p0,f32x16&p1,float mh){ const f32x2a m2={mh,mh};
;   #pragma unroll
;   for(int r=0;r<16;r+=2){ f32x2a a={p0[r],p0[r+1]}, b={p1[r],p1[r+1]}; a=a-m2; b=b-m2; p0[r]=a[0];p0[r+1]=a[1];p1[r]=b[0];p1[r+1]=b[1]; }
; }
.LBB0_1426:
	ds_read_b128 v[222:225], v184 offset:256
	ds_read_b128 v[226:229], v184 offset:384
	ds_read_b128 v[230:233], v184 offset:288
	ds_read_b128 v[242:245], v184 offset:416
	ds_read_b128 v[246:249], v184 offset:320
	ds_read_b128 v[250:253], v184 offset:448
	s_add_i32 s54, s62, 0x2000
	s_cmpk_lg_i32 s62, 0x4000
	s_cselect_b32 s95, s54, 0
	v_add_u32_e32 v4, s97, v219
	ds_read_b64_tr_b16 v[160:161], v4 offset:24576
	ds_read_b64_tr_b16 v[162:163], v4 offset:25088
	v_add_f32_e32 v2, v64, v65
	v_add_f32_e32 v2, v66, v2
	v_add_f32_e32 v2, v67, v2
	v_add_f32_e32 v2, v68, v2
	v_add_f32_e32 v2, v69, v2
	v_cvt_pk_bf16_f32 v132, v64, v65
	v_cvt_pk_bf16_f32 v133, v66, v67
	s_waitcnt lgkmcnt(9)
	v_mfma_f32_32x32x16_bf16 v[80:95], v[80:83], v[140:143], 0
	ds_read_b64_tr_b16 v[156:157], v4 offset:28672
	ds_read_b64_tr_b16 v[158:159], v4 offset:29184
	v_add_f32_e32 v2, v70, v2
	v_add_f32_e32 v2, v71, v2
	v_add_f32_e32 v2, v72, v2
	v_add_f32_e32 v2, v73, v2
	v_cvt_pk_bf16_f32 v134, v68, v69
	v_cvt_pk_bf16_f32 v135, v70, v71
	s_waitcnt lgkmcnt(10)
	v_mfma_f32_32x32x16_bf16 v[96:111], v[96:99], v[140:143], 0
	ds_read_b64_tr_b16 v[152:153], v4 offset:25600
	ds_read_b64_tr_b16 v[154:155], v4 offset:26112
	v_add_f32_e32 v2, v74, v2
	v_add_f32_e32 v2, v75, v2
	v_add_f32_e32 v2, v76, v2
	v_add_f32_e32 v2, v77, v2
	v_cvt_pk_bf16_f32 v124, v72, v73
	v_cvt_pk_bf16_f32 v125, v74, v75
	s_waitcnt lgkmcnt(11)
	v_mfma_f32_32x32x16_bf16 v[80:95], v[148:151], v[136:139], v[80:95]
	ds_read_b64_tr_b16 v[148:149], v4 offset:29696
	ds_read_b64_tr_b16 v[150:151], v4 offset:30208
	v_add_f32_e32 v2, v78, v2
	v_add_f32_e32 v2, v79, v2
	v_add_f32_e32 v2, v48, v2
	v_add_f32_e32 v2, v49, v2
	v_cvt_pk_bf16_f32 v126, v76, v77
	v_cvt_pk_bf16_f32 v127, v78, v79
	s_waitcnt lgkmcnt(12)
	v_mfma_f32_32x32x16_bf16 v[96:111], v[144:147], v[136:139], v[96:111]
	ds_read_b64_tr_b16 v[144:145], v4 offset:26624
	ds_read_b64_tr_b16 v[146:147], v4 offset:27136
	v_add_f32_e32 v2, v50, v2
	v_add_f32_e32 v2, v51, v2
	v_add_f32_e32 v2, v52, v2
	v_add_f32_e32 v2, v53, v2
	v_cvt_pk_bf16_f32 v116, v48, v49
	v_cvt_pk_bf16_f32 v117, v50, v51
	s_waitcnt lgkmcnt(13)
	v_mfma_f32_32x32x16_bf16 v[80:95], v[176:179], v[128:131], v[80:95]
	ds_read_b64_tr_b16 v[10:11], v4 offset:30720
	ds_read_b64_tr_b16 v[12:13], v4 offset:31232
	v_add_f32_e32 v2, v54, v2
	v_add_f32_e32 v2, v55, v2
	v_add_f32_e32 v2, v56, v2
	v_add_f32_e32 v2, v57, v2
	v_cvt_pk_bf16_f32 v118, v52, v53
	v_cvt_pk_bf16_f32 v119, v54, v55
	s_waitcnt lgkmcnt(14)
	v_mfma_f32_32x32x16_bf16 v[96:111], v[168:171], v[128:131], v[96:111]
	ds_read_b64_tr_b16 v[6:7], v4 offset:27648
	ds_read_b64_tr_b16 v[8:9], v4 offset:28160
	v_add_f32_e32 v2, v58, v2
	v_add_f32_e32 v2, v59, v2
	v_add_f32_e32 v2, v60, v2
	v_add_f32_e32 v14, v61, v2
	v_cvt_pk_bf16_f32 v112, v56, v57
	v_cvt_pk_bf16_f32 v113, v58, v59
	s_waitcnt lgkmcnt(14)
	v_mfma_f32_32x32x16_bf16 v[80:95], v[172:175], v[120:123], v[80:95]
	ds_read_b64_tr_b16 v[2:3], v4 offset:31744
	ds_read_b64_tr_b16 v[4:5], v4 offset:32256
	v_add_f32_e32 v14, v62, v14
	v_add_f32_e32 v14, v63, v14
	v_add_f32_e32 v64, 0, v14
	v_cvt_pk_bf16_f32 v114, v60, v61
	v_cvt_pk_bf16_f32 v115, v62, v63
	v_mfma_f32_32x32x16_bf16 v[96:111], v[164:167], v[120:123], v[96:111]
	s_add_i32 s54, s62, s66
	s_mov_b32 s55, m0
	s_mov_b32 m0, s54
	s_nop 0
	global_load_lds_dwordx4 v[182:183], off
	s_mov_b32 m0, s55
	s_add_i32 s54, s95, s67
	s_mov_b32 s55, m0
	s_mov_b32 m0, s54
	s_nop 0
	global_load_lds_dwordx4 v[180:181], off
	s_mov_b32 m0, s55
	ds_read_b128 v[48:51], v184 offset:352
	ds_read_b128 v[52:55], v184 offset:480
	s_waitcnt lgkmcnt(2)
	v_add_f32_e32 v80, v80, v222
	v_add_f32_e32 v81, v81, v223
	v_add_f32_e32 v82, v82, v224
	v_add_f32_e32 v83, v83, v225
	v_add_f32_e32 v96, v96, v226
	v_add_f32_e32 v97, v97, v227
	v_add_f32_e32 v98, v98, v228
	v_add_f32_e32 v99, v99, v229
	v_add_f32_e32 v84, v84, v230
	v_add_f32_e32 v85, v85, v231
	v_add_f32_e32 v86, v86, v232
	v_add_f32_e32 v87, v87, v233
	v_add_f32_e32 v100, v100, v242
	v_add_f32_e32 v101, v101, v243
	v_add_f32_e32 v102, v102, v244
	v_add_f32_e32 v103, v103, v245
	v_add_f32_e32 v88, v88, v246
	v_add_f32_e32 v89, v89, v247
	v_add_f32_e32 v90, v90, v248
	v_add_f32_e32 v91, v91, v249
	v_add_f32_e32 v104, v104, v250
	v_add_f32_e32 v105, v105, v251
	v_add_f32_e32 v106, v106, v252
	v_add_f32_e32 v107, v107, v253
	s_waitcnt lgkmcnt(1)
	v_add_f32_e32 v92, v92, v48
	v_add_f32_e32 v93, v93, v49
	v_add_f32_e32 v94, v94, v50
	v_add_f32_e32 v95, v95, v51
	s_waitcnt lgkmcnt(0)
	v_add_f32_e32 v108, v108, v52
	v_add_f32_e32 v109, v109, v53
	v_add_f32_e32 v110, v110, v54
	v_add_f32_e32 v111, v111, v55
	s_nop 0
	s_nop 0
	v_sub_f32_e32 v48, v80, v196
	v_sub_f32_e32 v49, v81, v196
	v_sub_f32_e32 v14, v96, v196
	v_sub_f32_e32 v15, v97, v196
	v_sub_f32_e32 v66, v82, v196
	v_sub_f32_e32 v67, v83, v196
	v_sub_f32_e32 v50, v98, v196
	v_sub_f32_e32 v51, v99, v196
	v_max_f32_e32 v65, v48, v49
	v_sub_f32_e32 v68, v84, v196
	v_sub_f32_e32 v69, v85, v196
	v_sub_f32_e32 v70, v86, v196
	v_sub_f32_e32 v71, v87, v196
	v_max3_f32 v80, v66, v67, v15
	v_max3_f32 v65, v65, v14, v50
	v_sub_f32_e32 v52, v100, v196
	v_sub_f32_e32 v53, v101, v196
	v_sub_f32_e32 v54, v102, v196
	v_sub_f32_e32 v55, v103, v196
	v_max3_f32 v65, v65, v51, v68
	v_max3_f32 v80, v80, v70, v71
	v_sub_f32_e32 v72, v88, v196
	v_sub_f32_e32 v73, v89, v196
	v_sub_f32_e32 v74, v90, v196
	v_sub_f32_e32 v75, v91, v196
	v_max3_f32 v65, v65, v69, v52
	v_max3_f32 v80, v80, v54, v55
	v_sub_f32_e32 v56, v104, v196
	v_sub_f32_e32 v57, v105, v196
	v_sub_f32_e32 v58, v106, v196
	v_sub_f32_e32 v59, v107, v196
	v_max3_f32 v65, v65, v53, v72
	v_max3_f32 v80, v80, v74, v75
	v_sub_f32_e32 v76, v92, v196
	v_sub_f32_e32 v77, v93, v196
	v_sub_f32_e32 v78, v94, v196
	v_sub_f32_e32 v79, v95, v196
	v_max3_f32 v65, v65, v73, v56
	v_max3_f32 v80, v80, v58, v59
	v_sub_f32_e32 v60, v108, v196
	v_sub_f32_e32 v61, v109, v196
	v_sub_f32_e32 v62, v110, v196
	v_sub_f32_e32 v63, v111, v196
	v_max3_f32 v65, v65, v57, v76
	v_max3_f32 v80, v80, v78, v79
	v_max3_f32 v65, v65, v77, v60
	v_max3_f32 v80, v80, v62, v63
	v_add_f32_e32 v220, v0, v64
	v_max3_f32 v0, v65, v61, v80
	v_mov_b32_e32 v64, v0
	s_nop 1
	v_permlane32_swap_b32_e32 v0, v64
	v_max_f32_e32 v64, v64, v64
	v_max_f32_e32 v0, v0, v0
	v_max_f32_e32 v0, v0, v64
	v_cmp_lt_f32_e32 vcc, s85, v0
	s_cmp_lg_u64 vcc, 0
	s_cselect_b64 s[54:55], -1, 0
	s_cbranch_vccnz .LBB0_1434

; __device__ __forceinline__ void submh(f32x16&p0,f32x16&p1,float mh){ const f32x2a m2={mh,mh};
;   #pragma unroll
;   for(int r=0;r<16;r+=2){ f32x2a a={p0[r],p0[r+1]}, b={p1[r],p1[r+1]}; a=a-m2; b=b-m2; p0[r]=a[0];p0[r+1]=a[1];p1[r]=b[0];p1[r+1]=b[1]; }
; }
.LBB0_1509:
	s_lshl_b32 s10, s10, 1
	v_add_u32_e32 v212, s10, v249
	ds_read_b64_tr_b16 v[208:209], v212 offset:24576
	ds_read_b64_tr_b16 v[210:211], v212 offset:25088
	v_add_f32_e32 v0, v96, v97
	v_add_f32_e32 v0, v98, v0
	v_add_f32_e32 v0, v99, v0
	v_add_f32_e32 v0, v100, v0
	v_add_f32_e32 v0, v101, v0
	v_cvt_pk_bf16_f32 v156, v96, v97
	v_cvt_pk_bf16_f32 v157, v98, v99
	v_mfma_f32_32x32x16_bf16 v[112:127], v[204:207], v[172:175], 0
	ds_read_b64_tr_b16 v[204:205], v212 offset:28672
	ds_read_b64_tr_b16 v[206:207], v212 offset:29184
	v_add_f32_e32 v0, v102, v0
	v_add_f32_e32 v0, v103, v0
	v_add_f32_e32 v0, v104, v0
	v_add_f32_e32 v0, v105, v0
	v_cvt_pk_bf16_f32 v158, v100, v101
	v_cvt_pk_bf16_f32 v159, v102, v103
	v_mfma_f32_32x32x16_bf16 v[128:143], v[200:203], v[172:175], 0
	ds_read_b64_tr_b16 v[10:11], v212 offset:25600
	ds_read_b64_tr_b16 v[12:13], v212 offset:26112
	v_add_f32_e32 v0, v106, v0
	v_add_f32_e32 v0, v107, v0
	v_add_f32_e32 v0, v108, v0
	v_add_f32_e32 v0, v109, v0
	v_cvt_pk_bf16_f32 v152, v104, v105
	v_cvt_pk_bf16_f32 v153, v106, v107
	v_mfma_f32_32x32x16_bf16 v[112:127], v[196:199], v[168:171], v[112:127]
	ds_read_b64_tr_b16 v[6:7], v212 offset:29696
	ds_read_b64_tr_b16 v[8:9], v212 offset:30208
	v_add_f32_e32 v0, v110, v0
	v_add_f32_e32 v0, v111, v0
	v_add_f32_e32 v0, v80, v0
	v_add_f32_e32 v0, v81, v0
	v_cvt_pk_bf16_f32 v154, v108, v109
	v_cvt_pk_bf16_f32 v155, v110, v111
	v_mfma_f32_32x32x16_bf16 v[128:143], v[192:195], v[168:171], v[128:143]
	ds_read_b64_tr_b16 v[2:3], v212 offset:26624
	ds_read_b64_tr_b16 v[4:5], v212 offset:27136
	v_add_f32_e32 v0, v82, v0
	v_add_f32_e32 v0, v83, v0
	v_add_f32_e32 v0, v84, v0
	v_add_f32_e32 v0, v85, v0
	v_cvt_pk_bf16_f32 v148, v80, v81
	v_cvt_pk_bf16_f32 v149, v82, v83
	v_mfma_f32_32x32x16_bf16 v[112:127], v[188:191], v[164:167], v[112:127]
	ds_read_b64_tr_b16 v[188:189], v212 offset:30720
	ds_read_b64_tr_b16 v[190:191], v212 offset:31232
	v_add_f32_e32 v0, v86, v0
	v_add_f32_e32 v0, v87, v0
	v_add_f32_e32 v0, v88, v0
	v_add_f32_e32 v0, v89, v0
	v_cvt_pk_bf16_f32 v150, v84, v85
	v_cvt_pk_bf16_f32 v151, v86, v87
	v_mfma_f32_32x32x16_bf16 v[128:143], v[184:187], v[164:167], v[128:143]
	ds_read_b64_tr_b16 v[192:193], v212 offset:27648
	ds_read_b64_tr_b16 v[194:195], v212 offset:28160
	v_add_f32_e32 v0, v90, v0
	v_add_f32_e32 v0, v91, v0
	v_add_f32_e32 v0, v92, v0
	v_add_f32_e32 v0, v93, v0
	v_cvt_pk_bf16_f32 v144, v88, v89
	v_cvt_pk_bf16_f32 v145, v90, v91
	v_mfma_f32_32x32x16_bf16 v[112:127], v[180:183], v[160:163], v[112:127]
	ds_read_b64_tr_b16 v[196:197], v212 offset:31744
	ds_read_b64_tr_b16 v[198:199], v212 offset:32256
	v_add_f32_e32 v0, v94, v0
	v_add_f32_e32 v0, v95, v0
	v_add_f32_e32 v0, 0, v0
	v_cvt_pk_bf16_f32 v146, v92, v93
	v_cvt_pk_bf16_f32 v147, v94, v95
	v_mfma_f32_32x32x16_bf16 v[128:143], v[176:179], v[160:163], v[128:143]
	s_lshl_b32 s48, s47, 13
	s_add_i32 s11, s89, s66
	s_mov_b32 m0, s11
	s_add_i32 s10, s48, 0x6000
	buffer_load_dwordx4 v246, s[12:15], s10 offen lds
	s_lshl_b32 s11, s46, 1
	s_add_i32 s10, s49, 0x4000
	s_add_i32 s42, s11, s67
	s_mov_b32 m0, s42
	s_nop 0
	buffer_load_dwordx4 v247, s[16:19], s10 offen lds
	s_add_i32 s10, s49, 0x4080
	s_add_i32 s11, s11, s53
	s_mov_b32 m0, s11
	s_nop 0
	buffer_load_dwordx4 v247, s[16:19], s10 offen lds
	v_add_f32_e64 v80, v112, -v228
	v_add_f32_e64 v81, v113, -v228
	v_sub_f32_e32 v14, v128, v228
	v_sub_f32_e32 v15, v129, v228
	v_sub_f32_e32 v98, v114, v228
	v_sub_f32_e32 v99, v115, v228
	v_sub_f32_e32 v82, v130, v228
	v_sub_f32_e32 v83, v131, v228
	v_max_f32_e32 v96, v80, v81
	v_sub_f32_e32 v100, v116, v228
	v_sub_f32_e32 v101, v117, v228
	v_sub_f32_e32 v102, v118, v228
	v_sub_f32_e32 v103, v119, v228
	v_max3_f32 v97, v98, v99, v15
	v_max3_f32 v96, v96, v14, v82
	v_sub_f32_e32 v84, v132, v228
	v_sub_f32_e32 v85, v133, v228
	v_sub_f32_e32 v86, v134, v228
	v_sub_f32_e32 v87, v135, v228
	v_max3_f32 v96, v96, v83, v100
	v_max3_f32 v97, v97, v102, v103
	v_sub_f32_e32 v104, v120, v228
	v_sub_f32_e32 v105, v121, v228
	v_sub_f32_e32 v106, v122, v228
	v_sub_f32_e32 v107, v123, v228
	v_max3_f32 v96, v96, v101, v84
	v_max3_f32 v97, v97, v86, v87
	v_sub_f32_e32 v88, v136, v228
	v_sub_f32_e32 v89, v137, v228
	v_sub_f32_e32 v90, v138, v228
	v_sub_f32_e32 v91, v139, v228
	v_max3_f32 v96, v96, v85, v104
	v_max3_f32 v97, v97, v106, v107
	v_sub_f32_e32 v108, v124, v228
	v_sub_f32_e32 v109, v125, v228
	v_sub_f32_e32 v110, v126, v228
	v_sub_f32_e32 v111, v127, v228
	v_max3_f32 v96, v96, v105, v88
	v_max3_f32 v97, v97, v90, v91
	v_sub_f32_e32 v92, v140, v228
	v_sub_f32_e32 v93, v141, v228
	v_sub_f32_e32 v94, v142, v228
	v_sub_f32_e32 v95, v143, v228
	v_max3_f32 v96, v96, v89, v108
	v_max3_f32 v97, v97, v110, v111
	v_max3_f32 v96, v96, v109, v92
	v_max3_f32 v97, v97, v94, v95
	v_max3_f32 v96, v96, v93, v97
	v_add_f32_e32 v0, v250, v0
	v_cmp_lt_f32_e32 vcc, s78, v96
	s_cmp_lg_u64 vcc, 0
	s_cselect_b64 s[10:11], -1, 0
	s_cbranch_vccnz .LBB0_1517

; __device__ __forceinline__ void submh(f32x16&p0,f32x16&p1,float mh){ const f32x2a m2={mh,mh};
;   #pragma unroll
;   for(int r=0;r<16;r+=2){ f32x2a a={p0[r],p0[r+1]}, b={p1[r],p1[r+1]}; a=a-m2; b=b-m2; p0[r]=a[0];p0[r+1]=a[1];p1[r]=b[0];p1[r+1]=b[1]; }
; }
.LBB0_1512:
	s_add_i32 s10, s46, 0x2000
	s_cmpk_lg_i32 s46, 0x4000
	s_cselect_b32 s87, s10, 0
	s_lshl_b32 s10, s89, 1
	v_add_u32_e32 v14, s10, v249
	ds_read_b64_tr_b16 v[192:193], v14 offset:24576
	ds_read_b64_tr_b16 v[194:195], v14 offset:25088
	v_add_f32_e32 v15, v96, v97
	v_add_f32_e32 v15, v98, v15
	v_add_f32_e32 v15, v99, v15
	v_add_f32_e32 v15, v100, v15
	v_add_f32_e32 v15, v101, v15
	v_cvt_pk_bf16_f32 v156, v96, v97
	v_cvt_pk_bf16_f32 v157, v98, v99
	v_mfma_f32_32x32x16_bf16 v[112:127], v[112:115], v[172:175], 0
	ds_read_b64_tr_b16 v[196:197], v14 offset:28672
	ds_read_b64_tr_b16 v[198:199], v14 offset:29184
	v_add_f32_e32 v15, v102, v15
	v_add_f32_e32 v15, v103, v15
	v_add_f32_e32 v15, v104, v15
	v_add_f32_e32 v15, v105, v15
	v_cvt_pk_bf16_f32 v158, v100, v101
	v_cvt_pk_bf16_f32 v159, v102, v103
	v_mfma_f32_32x32x16_bf16 v[128:143], v[128:131], v[172:175], 0
	ds_read_b64_tr_b16 v[188:189], v14 offset:25600
	ds_read_b64_tr_b16 v[190:191], v14 offset:26112
	v_add_f32_e32 v15, v106, v15
	v_add_f32_e32 v15, v107, v15
	v_add_f32_e32 v15, v108, v15
	v_add_f32_e32 v15, v109, v15
	v_cvt_pk_bf16_f32 v152, v104, v105
	v_cvt_pk_bf16_f32 v153, v106, v107
	v_mfma_f32_32x32x16_bf16 v[112:127], v[184:187], v[168:171], v[112:127]
	ds_read_b64_tr_b16 v[184:185], v14 offset:29696
	ds_read_b64_tr_b16 v[186:187], v14 offset:30208
	v_add_f32_e32 v15, v110, v15
	v_add_f32_e32 v15, v111, v15
	v_add_f32_e32 v15, v80, v15
	v_add_f32_e32 v15, v81, v15
	v_cvt_pk_bf16_f32 v154, v108, v109
	v_cvt_pk_bf16_f32 v155, v110, v111
	v_mfma_f32_32x32x16_bf16 v[128:143], v[176:179], v[168:171], v[128:143]
	ds_read_b64_tr_b16 v[176:177], v14 offset:26624
	ds_read_b64_tr_b16 v[178:179], v14 offset:27136
	v_add_f32_e32 v15, v82, v15
	v_add_f32_e32 v15, v83, v15
	v_add_f32_e32 v15, v84, v15
	v_add_f32_e32 v15, v85, v15
	v_cvt_pk_bf16_f32 v148, v80, v81
	v_cvt_pk_bf16_f32 v149, v82, v83
	v_mfma_f32_32x32x16_bf16 v[112:127], v[180:183], v[164:167], v[112:127]
	ds_read_b64_tr_b16 v[208:209], v14 offset:30720
	ds_read_b64_tr_b16 v[210:211], v14 offset:31232
	v_add_f32_e32 v15, v86, v15
	v_add_f32_e32 v15, v87, v15
	v_add_f32_e32 v15, v88, v15
	v_add_f32_e32 v15, v89, v15
	v_cvt_pk_bf16_f32 v150, v84, v85
	v_cvt_pk_bf16_f32 v151, v86, v87
	v_mfma_f32_32x32x16_bf16 v[128:143], v[6:9], v[164:167], v[128:143]
	ds_read_b64_tr_b16 v[6:7], v14 offset:27648
	ds_read_b64_tr_b16 v[8:9], v14 offset:28160
	v_add_f32_e32 v15, v90, v15
	v_add_f32_e32 v15, v91, v15
	v_add_f32_e32 v15, v92, v15
	v_add_f32_e32 v15, v93, v15
	v_cvt_pk_bf16_f32 v144, v88, v89
	v_cvt_pk_bf16_f32 v145, v90, v91
	v_mfma_f32_32x32x16_bf16 v[112:127], v[10:13], v[160:163], v[112:127]
	ds_read_b64_tr_b16 v[10:11], v14 offset:31744
	ds_read_b64_tr_b16 v[12:13], v14 offset:32256
	v_add_f32_e32 v15, v94, v15
	v_add_f32_e32 v15, v95, v15
	v_add_f32_e32 v15, 0, v15
	v_cvt_pk_bf16_f32 v146, v92, v93
	v_cvt_pk_bf16_f32 v147, v94, v95
	v_mfma_f32_32x32x16_bf16 v[128:143], v[2:5], v[160:163], v[128:143]
	s_add_i32 s10, s46, s66
	s_mov_b32 m0, s10
	s_add_i32 s48, s48, 0x8000
	buffer_load_dwordx4 v246, s[12:15], s48 offen lds
	s_lshl_b32 s10, s87, 1
	s_add_i32 s89, s49, 0x8000
	s_add_i32 s11, s10, s67
	s_mov_b32 m0, s11
	s_nop 0
	buffer_load_dwordx4 v247, s[16:19], s89 offen lds
	s_add_i32 s11, s49, 0x8080
	s_add_i32 s10, s10, s53
	s_mov_b32 m0, s10
	s_nop 0
	buffer_load_dwordx4 v247, s[16:19], s11 offen lds
	v_add_f32_e64 v4, v112, -v228
	v_add_f32_e64 v5, v113, -v228
	v_sub_f32_e32 v2, v128, v228
	v_sub_f32_e32 v3, v129, v228
	v_sub_f32_e32 v98, v114, v228
	v_sub_f32_e32 v99, v115, v228
	v_sub_f32_e32 v82, v130, v228
	v_sub_f32_e32 v83, v131, v228
	v_max_f32_e32 v80, v4, v5
	v_sub_f32_e32 v100, v116, v228
	v_sub_f32_e32 v101, v117, v228
	v_sub_f32_e32 v102, v118, v228
	v_sub_f32_e32 v103, v119, v228
	v_max3_f32 v81, v98, v99, v3
	v_max3_f32 v80, v80, v2, v82
	v_sub_f32_e32 v84, v132, v228
	v_sub_f32_e32 v85, v133, v228
	v_sub_f32_e32 v86, v134, v228
	v_sub_f32_e32 v87, v135, v228
	v_max3_f32 v80, v80, v83, v100
	v_max3_f32 v81, v81, v102, v103
	v_sub_f32_e32 v104, v120, v228
	v_sub_f32_e32 v105, v121, v228
	v_sub_f32_e32 v106, v122, v228
	v_sub_f32_e32 v107, v123, v228
	v_max3_f32 v80, v80, v101, v84
	v_max3_f32 v81, v81, v86, v87
	v_sub_f32_e32 v88, v136, v228
	v_sub_f32_e32 v89, v137, v228
	v_sub_f32_e32 v90, v138, v228
	v_sub_f32_e32 v91, v139, v228
	v_max3_f32 v80, v80, v85, v104
	v_max3_f32 v81, v81, v106, v107
	v_sub_f32_e32 v108, v124, v228
	v_sub_f32_e32 v109, v125, v228
	v_sub_f32_e32 v110, v126, v228
	v_sub_f32_e32 v111, v127, v228
	v_max3_f32 v80, v80, v105, v88
	v_max3_f32 v81, v81, v90, v91
	v_sub_f32_e32 v92, v140, v228
	v_sub_f32_e32 v93, v141, v228
	v_sub_f32_e32 v94, v142, v228
	v_sub_f32_e32 v95, v143, v228
	v_max3_f32 v80, v80, v89, v108
	v_max3_f32 v81, v81, v110, v111
	v_max3_f32 v80, v80, v109, v92
	v_max3_f32 v81, v81, v94, v95
	v_add_f32_e32 v250, v0, v15
	v_max3_f32 v0, v80, v93, v81
	v_cmp_lt_f32_e32 vcc, s78, v0
	s_cmp_lg_u64 vcc, 0
	s_cselect_b64 s[10:11], -1, 0
	s_cbranch_vccnz .LBB0_1520
